# v048_attnk
# baseline (speedup 1.0000x reference)
; __device__ __forceinline__ void attn_wave_item(const Params& p, int witem, const int tidx) {
;     ...
;     u32x4 vf[8], kn[8];
;     {
;       const int tn = tile > 0 ? tile - 1 : 0;
;       const char* vp = vbase + (size_t)tile * 8192;
;       const char* kp = kbase + (size_t)tn * 8192;
; #pragma unroll
;       for (int i = 0; i < 8; ++i) vf[i] = *reinterpret_cast<const u32x4*>(vp + i * 1024);
; #pragma unroll
;       for (int ks = 0; ks < 8; ++ks) kn[ks] = *reinterpret_cast<const u32x4*>(kp + ks * 1024);
;     }
;     __builtin_amdgcn_sched_barrier(0);
;     f32x16 S, S2;
; #pragma unroll
;     for (int i = 0; i < 16; ++i) { S[i] = 0.f; S2[i] = 0.f; }
; #pragma unroll
;     for (int ks = 0; ks < 8; ks += 2) {
;       u32x4 qa = *reinterpret_cast<const u32x4*>(qlds + ks * 1024);
;       u32x4 qb = *reinterpret_cast<const u32x4*>(qlds + (ks + 1) * 1024);
;       S = __builtin_amdgcn_mfma_f32_32x32x16_bf16(as_bf16x8(kf[ks]), as_bf16x8(qa), S, 0, 0, 0);
;       S2 = __builtin_amdgcn_mfma_f32_32x32x16_bf16(as_bf16x8(kf[ks + 1]), as_bf16x8(qb), S2, 0, 0, 0);
;     }
; #pragma unroll
;     for (int i = 0; i < 16; ++i) S[i] += S2[i];
;     const bool diag = (tile == qt);
;     float be[16], om[16];
; #pragma unroll
;     for (int r = 0; r < 16; ++r) {
;       float z = S[r];
;       float e = __builtin_amdgcn_exp2f(-fabsf(z));
;       float rr = __builtin_amdgcn_rcpf(1.f + e);
;       float sm = e * rr;
;       int kl = (r & 3) + 8 * (r >> 2) + 4 * half;
;       bool v = !diag || (kl < n);
;       bool pos = z >= 0.f;
;       be[r] = v ? (pos ? rr : sm) : 0.f;
;       om[r] = v ? (pos ? sm : rr) : 1.f;
;     }
.LBB0_119:
	ds_read_b128 v[226:229], v173
	ds_read_b128 v[84:87], v173 offset:1024
	ds_read_b128 v[204:207], v173 offset:2048
	ds_read_b128 v[222:225], v173 offset:3072
	ds_read_b128 v[230:233], v173 offset:4096
	ds_read_b128 v[234:237], v173 offset:5120
	ds_read_b128 v[238:241], v173 offset:6144
	ds_read_b128 v[242:245], v173 offset:7168
	v_lshl_add_u64 v[68:69], v[174:175], 0, s[48:49]
	s_mov_b32 s42, 0x20900000
	v_add_co_u32_e64 v72, s[42:43], s42, v68
	v_sub_u32_e64 v162, v169, 1 clamp
	s_nop 0
	v_addc_co_u32_e64 v73, s[42:43], 0, v69, s[42:43]
	s_mov_b32 s42, 0x20901000
	s_nop 0
	v_add_co_u32_e64 v68, s[42:43], s42, v68
	v_lshlrev_b64 v[70:71], 13, v[162:163]
	s_nop 0
	v_addc_co_u32_e64 v69, s[42:43], 0, v69, s[42:43]
	global_load_dwordx4 v[154:157], v[72:73], off offset:1024
	global_load_dwordx4 v[150:153], v[72:73], off offset:2048
	global_load_dwordx4 v[142:145], v[72:73], off offset:3072
	global_load_dwordx4 v[158:161], v[68:69], off offset:-4096
	global_load_dwordx4 v[146:149], v[68:69], off
	global_load_dwordx4 v[138:141], v[68:69], off offset:1024
	global_load_dwordx4 v[134:137], v[68:69], off offset:2048
	global_load_dwordx4 v[130:133], v[68:69], off offset:3072
	v_lshl_add_u64 v[246:247], v[170:171], 0, v[70:71]
	v_add_co_u32_e64 v248, s[42:43], s58, v246
	s_nop 1
	v_addc_co_u32_e64 v249, s[42:43], 0, v247, s[42:43]
	s_waitcnt vmcnt(8)
	s_cmp_lg_u32 s48, 0
	s_cselect_b64 s[50:51], -1, 0
	s_waitcnt lgkmcnt(7)
	s_setprio 1
	v_mfma_f32_32x32x16_bf16 v[64:79], v[98:101], v[226:229], 0
	s_or_b64 s[44:45], s[6:7], s[50:51]
	s_waitcnt lgkmcnt(6)
	v_mfma_f32_32x32x16_bf16 v[80:95], v[102:105], v[84:87], 0
	s_waitcnt lgkmcnt(5)
	v_mfma_f32_32x32x16_bf16 v[64:79], v[106:109], v[204:207], v[64:79]
	s_waitcnt lgkmcnt(4)
	v_mfma_f32_32x32x16_bf16 v[80:95], v[110:113], v[222:225], v[80:95]
	s_waitcnt lgkmcnt(3)
	v_mfma_f32_32x32x16_bf16 v[64:79], v[114:117], v[230:233], v[64:79]
	s_waitcnt lgkmcnt(2)
	v_mfma_f32_32x32x16_bf16 v[80:95], v[118:121], v[234:237], v[80:95]
	s_waitcnt lgkmcnt(1)
	v_mfma_f32_32x32x16_bf16 v[64:79], v[122:125], v[238:241], v[64:79]
	s_waitcnt lgkmcnt(0)
	v_mfma_f32_32x32x16_bf16 v[80:95], v[126:129], v[242:245], v[80:95]
	s_setprio 0
	global_load_dwordx4 v[98:101], v[246:247], off
	global_load_dwordx4 v[102:105], v[246:247], off offset:1024
	global_load_dwordx4 v[106:109], v[246:247], off offset:2048
	global_load_dwordx4 v[110:113], v[246:247], off offset:3072
	global_load_dwordx4 v[114:117], v[248:249], off
	global_load_dwordx4 v[118:121], v[248:249], off offset:1024
	global_load_dwordx4 v[122:125], v[248:249], off offset:2048
	global_load_dwordx4 v[126:129], v[248:249], off offset:3072
	s_nop 3
	v_add_f32_e32 v64, v64, v80
	v_exp_f32_e64 v80, -|v64|
	v_add_f32_e32 v65, v65, v81
	v_add_f32_e32 v66, v66, v82
	v_exp_f32_e64 v82, -|v65|
	v_add_f32_e32 v81, 1.0, v80
	v_rcp_f32_e32 v81, v81
	v_add_f32_e32 v67, v67, v83
	v_add_f32_e32 v83, 1.0, v82
	v_cmp_le_f32_e64 s[42:43], 0, v64
	v_mul_f32_e32 v80, v80, v81
	v_rcp_f32_e32 v83, v83
	v_cndmask_b32_e64 v64, v80, v81, s[42:43]
	v_add_f32_e32 v68, v68, v84
	v_cndmask_b32_e64 v84, 0, v64, s[44:45]
	v_cndmask_b32_e64 v64, v81, v80, s[42:43]
	v_exp_f32_e64 v81, -|v66|
	v_cndmask_b32_e64 v80, 1.0, v64, s[44:45]
	v_mul_f32_e32 v64, v82, v83
	v_cmp_le_f32_e64 s[42:43], 0, v65
	s_or_b64 s[44:45], s[8:9], s[50:51]
	v_add_f32_e32 v69, v69, v85
	v_cndmask_b32_e64 v65, v64, v83, s[42:43]
	v_cndmask_b32_e64 v64, v83, v64, s[42:43]
	v_cndmask_b32_e64 v82, 0, v65, s[44:45]
	v_add_f32_e32 v65, 1.0, v81
	v_cndmask_b32_e64 v83, 1.0, v64, s[44:45]
	v_exp_f32_e64 v64, -|v67|
	v_rcp_f32_e32 v65, v65
	v_cmp_le_f32_e64 s[42:43], 0, v66
	s_or_b64 s[44:45], s[10:11], s[50:51]
	v_add_f32_e32 v85, 1.0, v64
	v_mul_f32_e32 v81, v81, v65
	v_rcp_f32_e32 v85, v85
	v_cndmask_b32_e64 v66, v81, v65, s[42:43]
	v_cndmask_b32_e64 v65, v65, v81, s[42:43]
	v_cndmask_b32_e64 v81, 1.0, v65, s[44:45]
	v_exp_f32_e64 v65, -|v68|
	v_mul_f32_e32 v64, v64, v85
	v_cmp_le_f32_e64 s[42:43], 0, v67
	v_exp_f32_e64 v67, -|v69|
	v_add_f32_e32 v70, v70, v86
	v_cndmask_b32_e64 v86, 0, v66, s[44:45]
	v_cndmask_b32_e64 v66, v64, v85, s[42:43]
	s_or_b64 s[44:45], s[12:13], s[50:51]
	v_add_f32_e32 v71, v71, v87
	v_cndmask_b32_e64 v87, 0, v66, s[44:45]
	v_add_f32_e32 v66, 1.0, v65
	v_rcp_f32_e32 v66, v66
	v_cndmask_b32_e64 v64, v85, v64, s[42:43]
	v_cmp_le_f32_e64 s[42:43], 0, v68
	v_add_f32_e32 v68, 1.0, v67
	v_rcp_f32_e32 v68, v68
	v_cndmask_b32_e64 v85, 1.0, v64, s[44:45]
	v_mul_f32_e32 v64, v65, v66
	v_cndmask_b32_e64 v65, v64, v66, s[42:43]
	s_or_b64 s[44:45], s[14:15], s[50:51]
	v_add_f32_e32 v72, v72, v88
	v_cndmask_b32_e64 v88, 0, v65, s[44:45]
	v_mul_f32_e32 v65, v67, v68
	v_exp_f32_e64 v67, -|v70|
	v_cndmask_b32_e64 v64, v66, v64, s[42:43]
	v_cmp_le_f32_e64 s[42:43], 0, v69
	v_cndmask_b32_e64 v64, 1.0, v64, s[44:45]
	s_or_b64 s[44:45], s[16:17], s[50:51]
	v_cndmask_b32_e64 v66, v65, v68, s[42:43]
	v_add_f32_e32 v73, v73, v89
	v_cndmask_b32_e64 v89, 0, v66, s[44:45]
	v_add_f32_e32 v66, 1.0, v67
	v_cndmask_b32_e64 v65, v68, v65, s[42:43]
	v_rcp_f32_e32 v69, v66
	v_cndmask_b32_e64 v66, 1.0, v65, s[44:45]
	v_exp_f32_e64 v65, -|v71|
	v_cmp_le_f32_e64 s[42:43], 0, v70
	v_mul_f32_e32 v67, v67, v69
	s_or_b64 s[44:45], s[18:19], s[50:51]
	v_add_f32_e32 v70, 1.0, v65
	v_rcp_f32_e32 v70, v70
	v_cndmask_b32_e64 v68, v67, v69, s[42:43]
	v_cndmask_b32_e64 v67, v69, v67, s[42:43]
	v_cndmask_b32_e64 v176, 1.0, v67, s[44:45]
	v_exp_f32_e64 v67, -|v72|
	v_mul_f32_e32 v65, v65, v70
	v_cmp_le_f32_e64 s[42:43], 0, v71
	v_add_f32_e32 v74, v74, v90
	v_cndmask_b32_e64 v90, 0, v68, s[44:45]
	v_cndmask_b32_e64 v68, v65, v70, s[42:43]
; __device__ __forceinline__ void attn_wave_item(const Params& p, int witem, const int tidx) {
;     ...
;     for (int r = 0; r < 16; ++r) {
;       float z = S[r];
;       float e = __builtin_amdgcn_exp2f(-fabsf(z));
;       float rr = __builtin_amdgcn_rcpf(1.f + e);
;       float sm = e * rr;
;       int kl = (r & 3) + 8 * (r >> 2) + 4 * half;
;       bool v = !diag || (kl < n);
;       bool pos = z >= 0.f;
;       be[r] = v ? (pos ? rr : sm) : 0.f;
;       om[r] = v ? (pos ? sm : rr) : 1.f;
;     }
;     float gp[4], pgp[4];
; #pragma unroll
;     for (int gi = 0; gi < 4; ++gi) {
;       gp[gi] = (om[4 * gi] * om[4 * gi + 1]) * (om[4 * gi + 2] * om[4 * gi + 3]);
;       pgp[gi] = __shfl_xor(gp[gi], 32, 64);
;     }
;     float w[16];
;     float run = R;
; #pragma unroll
;     ...
;       float a = (half == 0) ? (run * pgp[gi]) : run;
; #pragma unroll
;       for (int r = 3; r >= 0; --r) {
;         int ri = 4 * gi + r;
;         w[ri] = be[ri] * a;
;         a *= om[ri];
;       }
;       run *= gp[gi] * pgp[gi];
;     }
;     R = run;
;     __builtin_amdgcn_sched_barrier(0);
;     bf16x8 pf[2];
; #pragma unroll
;     for (int m = 0; m < 2; ++m) {
;       u32x4 t;
;       t.x = pack2(w[8 * m + 0], w[8 * m + 1]);
;       t.y = pack2(w[8 * m + 2], w[8 * m + 3]);
;       t.z = pack2(w[8 * m + 4], w[8 * m + 5]);
;       t.w = pack2(w[8 * m + 6], w[8 * m + 7]);
;       pf[m] = as_bf16x8(t);
;     }
; #pragma unroll
;     for (int dt = 0; dt < 4; ++dt)
; #pragma unroll
;       for (int m = 0; m < 2; ++m) O[dt] = __builtin_amdgcn_mfma_f32_32x32x16_bf16(as_bf16x8(vf[dt * 2 + m]), pf[m], O[dt], 0, 0, 0);
;     if (__all(R < 1.17549435e-38f)) break;
;     __builtin_amdgcn_sched_barrier(0);
; #pragma unroll
;     for (int i = 0; i < 8; ++i) kf[i] = kn[i];
;   }
	s_or_b64 s[44:45], s[20:21], s[50:51]
	v_cndmask_b32_e64 v71, 0, v68, s[44:45]
	v_add_f32_e32 v68, 1.0, v67
	v_cndmask_b32_e64 v65, v70, v65, s[42:43]
	v_rcp_f32_e32 v69, v68
	v_cndmask_b32_e64 v68, 1.0, v65, s[44:45]
	v_exp_f32_e64 v65, -|v73|
	v_cmp_le_f32_e64 s[42:43], 0, v72
	v_mul_f32_e32 v67, v67, v69
	s_or_b64 s[44:45], s[22:23], s[50:51]
	v_add_f32_e32 v72, 1.0, v65
	v_rcp_f32_e32 v72, v72
	v_cndmask_b32_e64 v70, v67, v69, s[42:43]
	v_cndmask_b32_e64 v67, v69, v67, s[42:43]
	v_cmp_le_f32_e64 s[42:43], 0, v73
	v_mul_f32_e32 v65, v65, v72
	v_add_f32_e32 v75, v75, v91
	v_cndmask_b32_e64 v91, 0, v70, s[44:45]
	v_cndmask_b32_e64 v67, 1.0, v67, s[44:45]
	v_exp_f32_e64 v69, -|v74|
	v_cndmask_b32_e64 v70, v65, v72, s[42:43]
	s_or_b64 s[44:45], s[24:25], s[50:51]
	v_cndmask_b32_e64 v65, v72, v65, s[42:43]
	v_add_f32_e32 v77, v77, v93
	v_cndmask_b32_e64 v93, 1.0, v65, s[44:45]
	v_exp_f32_e64 v65, -|v75|
	v_add_f32_e32 v76, v76, v92
	v_cndmask_b32_e64 v92, 0, v70, s[44:45]
	v_add_f32_e32 v70, 1.0, v69
	v_rcp_f32_e32 v70, v70
	v_add_f32_e32 v73, 1.0, v65
	v_rcp_f32_e32 v73, v73
	v_cmp_le_f32_e64 s[42:43], 0, v74
	v_mul_f32_e32 v69, v69, v70
	s_or_b64 s[44:45], s[26:27], s[50:51]
	v_cndmask_b32_e64 v72, v69, v70, s[42:43]
	v_cndmask_b32_e64 v69, v70, v69, s[42:43]
	v_mul_f32_e32 v65, v65, v73
	v_cmp_le_f32_e64 s[42:43], 0, v75
	v_add_f32_e32 v78, v78, v94
	v_add_f32_e32 v79, v79, v95
	v_cndmask_b32_e64 v94, 0, v72, s[44:45]
	v_cndmask_b32_e64 v95, 1.0, v69, s[44:45]
	v_exp_f32_e64 v69, -|v76|
	v_cndmask_b32_e64 v70, v65, v73, s[42:43]
	s_or_b64 s[44:45], s[28:29], s[50:51]
	v_cndmask_b32_e64 v65, v73, v65, s[42:43]
	v_cndmask_b32_e64 v179, 1.0, v65, s[44:45]
	v_exp_f32_e64 v65, -|v77|
	v_cndmask_b32_e64 v162, 0, v70, s[44:45]
	v_add_f32_e32 v70, 1.0, v69
	v_rcp_f32_e32 v70, v70
	v_add_f32_e32 v73, 1.0, v65
	v_rcp_f32_e32 v73, v73
	v_cmp_le_f32_e64 s[42:43], 0, v76
	v_mul_f32_e32 v69, v69, v70
	s_or_b64 s[44:45], s[30:31], s[50:51]
	v_cndmask_b32_e64 v72, v69, v70, s[42:43]
	v_cndmask_b32_e64 v69, v70, v69, s[42:43]
	v_mul_f32_e32 v65, v65, v73
	v_cmp_le_f32_e64 s[42:43], 0, v77
	v_cndmask_b32_e64 v74, 0, v72, s[44:45]
	v_cndmask_b32_e64 v69, 1.0, v69, s[44:45]
	v_exp_f32_e64 v70, -|v78|
	v_cndmask_b32_e64 v72, v65, v73, s[42:43]
	s_or_b64 s[44:45], s[34:35], s[50:51]
	v_cndmask_b32_e64 v65, v73, v65, s[42:43]
	v_cndmask_b32_e64 v73, 1.0, v65, s[44:45]
	v_exp_f32_e64 v65, -|v79|
	v_cndmask_b32_e64 v75, 0, v72, s[44:45]
	v_add_f32_e32 v72, 1.0, v70
	v_rcp_f32_e32 v72, v72
	v_add_f32_e32 v77, 1.0, v65
	v_rcp_f32_e32 v77, v77
	v_cmp_le_f32_e64 s[42:43], 0, v78
	v_mul_f32_e32 v70, v70, v72
	s_or_b64 s[44:45], s[36:37], s[50:51]
	v_cndmask_b32_e64 v76, v70, v72, s[42:43]
	v_cndmask_b32_e64 v70, v72, v70, s[42:43]
	v_mul_f32_e32 v65, v65, v77
	v_cmp_le_f32_e64 s[42:43], 0, v79
	v_cndmask_b32_e64 v76, 0, v76, s[44:45]
	v_cndmask_b32_e64 v78, 1.0, v70, s[44:45]
	v_cndmask_b32_e64 v70, v65, v77, s[42:43]
	s_or_b64 s[44:45], s[38:39], s[50:51]
	v_cndmask_b32_e64 v65, v77, v65, s[42:43]
	v_cndmask_b32_e64 v77, 1.0, v65, s[44:45]
	v_mul_f32_e32 v65, v69, v73
	v_mul_f32_e32 v69, v78, v77
	v_mul_f32_e32 v69, v65, v69
	v_cndmask_b32_e64 v79, 0, v70, s[44:45]
	v_mul_f32_e32 v70, v80, v83
	ds_bpermute_b32 v80, v178, v69
	v_mul_f32_e32 v65, v67, v93
	v_mul_f32_e32 v67, v95, v179
	v_mul_f32_e32 v65, v65, v67
	ds_bpermute_b32 v67, v178, v65
	s_waitcnt lgkmcnt(1)
	v_mul_f32_e32 v180, v177, v80
	v_cndmask_b32_e32 v180, v177, v180, vcc
	v_mul_f32_e32 v77, v180, v77
	v_mul_f32_e32 v76, v76, v77
	v_mul_f32_e32 v77, v78, v77
	v_mul_f32_e32 v73, v73, v77
	v_mul_f32_e32 v69, v69, v80
	v_mul_f32_e32 v78, v75, v77
	v_mul_f32_e32 v77, v74, v73
	v_pk_mul_f32 v[74:75], v[176:177], v[68:69]
	s_waitcnt lgkmcnt(0)
	v_pk_mul_f32 v[64:65], v[64:65], v[66:67]
	v_mul_f32_e32 v67, v75, v67
	v_pk_mul_f32 v[64:65], v[64:65], v[74:75]
	ds_bpermute_b32 v73, v178, v64
	v_cndmask_b32_e32 v67, v75, v67, vcc
	v_mul_f32_e32 v74, v162, v67
	v_mul_f32_e32 v67, v179, v67
	v_mul_f32_e32 v75, v94, v67
	v_mul_f32_e32 v67, v95, v67
	v_mul_f32_e32 v80, v92, v67
	v_mul_f32_e32 v67, v93, v67
	v_mul_f32_e32 v91, v91, v67
	s_waitcnt lgkmcnt(0)
	v_mul_f32_e32 v67, v65, v73
	v_cndmask_b32_e32 v67, v65, v67, vcc
	v_mul_f32_e32 v72, v81, v85
	v_mul_f32_e32 v92, v71, v67
	v_mov_b32_e32 v71, v64
	v_mul_f32_e32 v67, v68, v67
	v_pk_mul_f32 v[68:69], v[70:71], v[72:73]
	ds_bpermute_b32 v64, v178, v68
	v_mul_f32_e32 v90, v90, v67
	v_mul_f32_e32 v67, v176, v67
	v_mul_f32_e32 v70, v89, v67
	v_mul_f32_e32 v66, v66, v67
	s_waitcnt lgkmcnt(0)
	v_pk_mul_f32 v[72:73], v[68:69], v[64:65]
	v_mul_f32_e32 v79, v180, v79
	v_mul_f32_e32 v64, v73, v64
	v_cndmask_b32_e32 v64, v73, v64, vcc
	v_mul_f32_e32 v65, v87, v64
	v_mul_f32_e32 v64, v85, v64
	v_mul_f32_e32 v67, v86, v64
	v_mul_f32_e32 v64, v81, v64
	v_mul_f32_e32 v68, v82, v64
	v_mul_f32_e32 v64, v83, v64
	v_mul_f32_e32 v66, v88, v66
	v_mul_f32_e32 v64, v84, v64
	v_cvt_pk_bf16_f32 v64, v64, v68
	v_cvt_pk_bf16_f32 v65, v67, v65
	v_cvt_pk_bf16_f32 v66, v66, v70
	v_cvt_pk_bf16_f32 v67, v90, v92
	v_cvt_pk_bf16_f32 v68, v91, v80
	v_cvt_pk_bf16_f32 v69, v75, v74
	v_cvt_pk_bf16_f32 v70, v77, v78
	v_cvt_pk_bf16_f32 v71, v76, v79
	v_mul_f32_e32 v177, v72, v73
	s_waitcnt vmcnt(12)
	s_setprio 1
	v_mfma_f32_32x32x16_bf16 v[48:63], v[158:161], v[64:67], v[48:63]
	v_cmp_gt_f32_e64 s[42:43], s1, v177
	s_or_b64 s[92:93], s[92:93], exec
	s_mov_b64 s[44:45], -1
	s_cmp_lg_u64 s[42:43], exec
	v_mfma_f32_32x32x16_bf16 v[32:47], v[150:153], v[64:67], v[32:47]
	s_waitcnt vmcnt(11)
	v_mfma_f32_32x32x16_bf16 v[16:31], v[146:149], v[64:67], v[16:31]
	s_waitcnt vmcnt(9)
	v_mfma_f32_32x32x16_bf16 v[0:15], v[134:137], v[64:67], v[0:15]
	v_mfma_f32_32x32x16_bf16 v[48:63], v[154:157], v[68:71], v[48:63]
	v_mfma_f32_32x32x16_bf16 v[32:47], v[142:145], v[68:71], v[32:47]
	v_mfma_f32_32x32x16_bf16 v[16:31], v[138:141], v[68:71], v[16:31]
	s_waitcnt vmcnt(8)
	v_mfma_f32_32x32x16_bf16 v[0:15], v[130:133], v[68:71], v[0:15]
	s_setprio 0
	s_cbranch_scc1 .LBB0_117
	s_branch .LBB0_118
